# gemm_in ZGR/ZRW epilogue: bf16 pairs exchanged between neighbour lanes (DPP+v_perm), dword stores instead of short stores
# baseline (speedup 1.0000x reference)
; DI int crow(int reg, int h5) { return (reg & 3) + 8 * (reg >> 2) + 4 * h5; }
; template <int MTW> DI void gemm_in_phase(const Params& p, int l, int bid, int nb, char* smem) {
;     ...
;     } else {
;       u16* dstb; int ld, cb;
;       if (col0 < 3072) { dstb = ZGR; ld = 1024; cb = wcol - 2048; } else { dstb = ZRW; ld = RWB; cb = wcol - 3072; }
; #pragma unroll
;       for (int mt = 0; mt < MTW; ++mt)
; #pragma unroll
;         for (int nt = 0; nt < 2; ++nt)
; #pragma unroll
;           for (int i = 0; i < 16; ++i) {
;             const int row = row0 + wr * (32 * MTW) + mt * 32 + crow(i, h5);
;             dstb[(size_t)row * ld + cb + nt * 32 + c] = f2bf(acc[mt][nt][i]);
;           }
.LBB0_511:
	v_mov_b32_e32 v0, v196
	s_cmp_gt_i32 s15, 7
	s_waitcnt vmcnt(8)
	v_and_b32_e32 v139, 63, v0
	v_mov_b32_e32 v0, v196
	s_mov_b64 s[4:5], -1
	v_ashrrev_i32_e32 v0, 6, v0
	v_and_b32_e32 v138, 31, v139
	v_ashrrev_i32_e32 v142, 1, v0
	v_lshlrev_b32_e32 v0, 6, v0
	v_and_b32_e32 v132, 64, v0
	v_ashrrev_i32_e32 v141, 5, v139
	v_or_b32_e32 v140, s0, v132
	s_cbranch_scc0 .LBB0_645
	s_cmp_gt_u32 s15, 15
	s_cbranch_scc0 .LBB0_514
	s_mov_b32 s4, 0x14360000
	s_movk_i32 s1, 0x780
	s_movk_i32 s5, 0xf400
	s_cmp_lt_u32 s15, 24
	s_cselect_b32 s4, 0xfb60000, s4
	s_cselect_b32 s1, 0x400, s1
	s_cselect_b32 s5, 0xfffff800, s5
	v_and_b32_e32 v209, 1, v138
	v_lshlrev_b32_e32 v208, 7, v142
	v_lshl_add_u32 v208, v141, 2, v208
	v_add_u32_e32 v208, s44, v208
	v_add_u32_e32 v208, v208, v209
	v_mul_lo_u32 v208, v208, s1
	v_add_u32_e32 v210, s5, v140
	v_add_u32_e32 v210, v210, v138
	v_sub_u32_e32 v210, v210, v209
	v_add_lshl_u32 v222, v208, v210, 1
	v_mov_b32_e32 v221, 0x5040100
	v_mov_b32_e32 v211, 0x3020706
	v_cmp_eq_u32_e32 vcc, 1, v209
	s_add_u32 s4, s22, s4
	s_addc_u32 s5, s23, 0
	s_lshl_b32 s1, s1, 1
	v_cndmask_b32_e32 v221, v221, v211, vcc
	v_mov_b32_e32 v220, v222
	s_mul_i32 s0, s1, 2
	v_add_u32_e32 v223, s0, v222
	v_cvt_pk_bf16_f32 v208, v114, v115
	v_cvt_pk_bf16_f32 v209, v98, v99
	v_cvt_pk_bf16_f32 v210, v116, v117
	v_cvt_pk_bf16_f32 v211, v100, v101
	v_mov_b32_dpp v212, v208 quad_perm:[1,0,3,2] row_mask:0xf bank_mask:0xf
	v_mov_b32_dpp v213, v209 quad_perm:[1,0,3,2] row_mask:0xf bank_mask:0xf
	v_mov_b32_dpp v214, v210 quad_perm:[1,0,3,2] row_mask:0xf bank_mask:0xf
	v_mov_b32_dpp v215, v211 quad_perm:[1,0,3,2] row_mask:0xf bank_mask:0xf
	v_perm_b32 v216, v212, v208, v221
	v_perm_b32 v217, v213, v209, v221
	v_perm_b32 v218, v214, v210, v221
	v_perm_b32 v219, v215, v211, v221
	global_store_dword v220, v216, s[4:5]
	global_store_dword v220, v217, s[4:5] offset:64
	global_store_dword v223, v218, s[4:5]
	global_store_dword v223, v219, s[4:5] offset:64
	s_mul_i32 s0, s1, 8
	v_add_u32_e32 v220, s0, v222
	s_mul_i32 s0, s1, 10
	v_add_u32_e32 v223, s0, v222
	v_cvt_pk_bf16_f32 v208, v118, v119
	v_cvt_pk_bf16_f32 v209, v102, v103
	v_cvt_pk_bf16_f32 v210, v120, v121
	v_cvt_pk_bf16_f32 v211, v104, v105
	v_mov_b32_dpp v212, v208 quad_perm:[1,0,3,2] row_mask:0xf bank_mask:0xf
	v_mov_b32_dpp v213, v209 quad_perm:[1,0,3,2] row_mask:0xf bank_mask:0xf
	v_mov_b32_dpp v214, v210 quad_perm:[1,0,3,2] row_mask:0xf bank_mask:0xf
	v_mov_b32_dpp v215, v211 quad_perm:[1,0,3,2] row_mask:0xf bank_mask:0xf
	v_perm_b32 v216, v212, v208, v221
	v_perm_b32 v217, v213, v209, v221
	v_perm_b32 v218, v214, v210, v221
	v_perm_b32 v219, v215, v211, v221
	global_store_dword v220, v216, s[4:5]
	global_store_dword v220, v217, s[4:5] offset:64
	global_store_dword v223, v218, s[4:5]
	global_store_dword v223, v219, s[4:5] offset:64
	s_mul_i32 s0, s1, 16
	v_add_u32_e32 v220, s0, v222
	s_mul_i32 s0, s1, 18
	v_add_u32_e32 v223, s0, v222
	v_cvt_pk_bf16_f32 v208, v122, v123
	v_cvt_pk_bf16_f32 v209, v106, v107
	v_cvt_pk_bf16_f32 v210, v124, v125
	v_cvt_pk_bf16_f32 v211, v108, v109
	v_mov_b32_dpp v212, v208 quad_perm:[1,0,3,2] row_mask:0xf bank_mask:0xf
	v_mov_b32_dpp v213, v209 quad_perm:[1,0,3,2] row_mask:0xf bank_mask:0xf
	v_mov_b32_dpp v214, v210 quad_perm:[1,0,3,2] row_mask:0xf bank_mask:0xf
	v_mov_b32_dpp v215, v211 quad_perm:[1,0,3,2] row_mask:0xf bank_mask:0xf
	v_perm_b32 v216, v212, v208, v221
	v_perm_b32 v217, v213, v209, v221
	v_perm_b32 v218, v214, v210, v221
	v_perm_b32 v219, v215, v211, v221
	global_store_dword v220, v216, s[4:5]
	global_store_dword v220, v217, s[4:5] offset:64
	global_store_dword v223, v218, s[4:5]
	global_store_dword v223, v219, s[4:5] offset:64
	s_mul_i32 s0, s1, 24
	v_add_u32_e32 v220, s0, v222
	s_mul_i32 s0, s1, 26
	v_add_u32_e32 v223, s0, v222
	v_cvt_pk_bf16_f32 v208, v126, v127
	v_cvt_pk_bf16_f32 v209, v110, v111
	v_cvt_pk_bf16_f32 v210, v128, v129
	v_cvt_pk_bf16_f32 v211, v112, v113
	v_mov_b32_dpp v212, v208 quad_perm:[1,0,3,2] row_mask:0xf bank_mask:0xf
	v_mov_b32_dpp v213, v209 quad_perm:[1,0,3,2] row_mask:0xf bank_mask:0xf
	v_mov_b32_dpp v214, v210 quad_perm:[1,0,3,2] row_mask:0xf bank_mask:0xf
	v_mov_b32_dpp v215, v211 quad_perm:[1,0,3,2] row_mask:0xf bank_mask:0xf
	v_perm_b32 v216, v212, v208, v221
	v_perm_b32 v217, v213, v209, v221
	v_perm_b32 v218, v214, v210, v221
	v_perm_b32 v219, v215, v211, v221
	global_store_dword v220, v216, s[4:5]
	global_store_dword v220, v217, s[4:5] offset:64
	global_store_dword v223, v218, s[4:5]
	global_store_dword v223, v219, s[4:5] offset:64
	s_mul_i32 s0, s1, 32
	v_add_u32_e32 v220, s0, v222
	s_mul_i32 s0, s1, 34
	v_add_u32_e32 v223, s0, v222
	v_cvt_pk_bf16_f32 v208, v82, v83
	v_cvt_pk_bf16_f32 v209, v66, v67
	v_cvt_pk_bf16_f32 v210, v84, v85
	v_cvt_pk_bf16_f32 v211, v68, v69
	v_mov_b32_dpp v212, v208 quad_perm:[1,0,3,2] row_mask:0xf bank_mask:0xf
	v_mov_b32_dpp v213, v209 quad_perm:[1,0,3,2] row_mask:0xf bank_mask:0xf
	v_mov_b32_dpp v214, v210 quad_perm:[1,0,3,2] row_mask:0xf bank_mask:0xf
	v_mov_b32_dpp v215, v211 quad_perm:[1,0,3,2] row_mask:0xf bank_mask:0xf
	v_perm_b32 v216, v212, v208, v221
	v_perm_b32 v217, v213, v209, v221
	v_perm_b32 v218, v214, v210, v221
	v_perm_b32 v219, v215, v211, v221
	global_store_dword v220, v216, s[4:5]
	global_store_dword v220, v217, s[4:5] offset:64
	global_store_dword v223, v218, s[4:5]
	global_store_dword v223, v219, s[4:5] offset:64
	s_mul_i32 s0, s1, 40
	v_add_u32_e32 v220, s0, v222
	s_mul_i32 s0, s1, 42
	v_add_u32_e32 v223, s0, v222
	v_cvt_pk_bf16_f32 v208, v86, v87
	v_cvt_pk_bf16_f32 v209, v70, v71
	v_cvt_pk_bf16_f32 v210, v88, v89
	v_cvt_pk_bf16_f32 v211, v72, v73
; DI int crow(int reg, int h5) { return (reg & 3) + 8 * (reg >> 2) + 4 * h5; }
; template <int MTW> DI void gemm_in_phase(const Params& p, int l, int bid, int nb, char* smem) {
;     ...
; #pragma unroll
;       for (int mt = 0; mt < MTW; ++mt)
; #pragma unroll
;         for (int nt = 0; nt < 2; ++nt)
; #pragma unroll
;           for (int i = 0; i < 16; ++i) {
;             const int row = row0 + wr * (32 * MTW) + mt * 32 + crow(i, h5);
;             dstb[(size_t)row * ld + cb + nt * 32 + c] = f2bf(acc[mt][nt][i]);
;           }
	v_mov_b32_dpp v212, v208 quad_perm:[1,0,3,2] row_mask:0xf bank_mask:0xf
	v_mov_b32_dpp v213, v209 quad_perm:[1,0,3,2] row_mask:0xf bank_mask:0xf
	v_mov_b32_dpp v214, v210 quad_perm:[1,0,3,2] row_mask:0xf bank_mask:0xf
	v_mov_b32_dpp v215, v211 quad_perm:[1,0,3,2] row_mask:0xf bank_mask:0xf
	v_perm_b32 v216, v212, v208, v221
	v_perm_b32 v217, v213, v209, v221
	v_perm_b32 v218, v214, v210, v221
	v_perm_b32 v219, v215, v211, v221
	global_store_dword v220, v216, s[4:5]
	global_store_dword v220, v217, s[4:5] offset:64
	global_store_dword v223, v218, s[4:5]
	global_store_dword v223, v219, s[4:5] offset:64
	s_mul_i32 s0, s1, 48
	v_add_u32_e32 v220, s0, v222
	s_mul_i32 s0, s1, 50
	v_add_u32_e32 v223, s0, v222
	v_cvt_pk_bf16_f32 v208, v90, v91
	v_cvt_pk_bf16_f32 v209, v74, v75
	v_cvt_pk_bf16_f32 v210, v92, v93
	v_cvt_pk_bf16_f32 v211, v76, v77
	v_mov_b32_dpp v212, v208 quad_perm:[1,0,3,2] row_mask:0xf bank_mask:0xf
	v_mov_b32_dpp v213, v209 quad_perm:[1,0,3,2] row_mask:0xf bank_mask:0xf
	v_mov_b32_dpp v214, v210 quad_perm:[1,0,3,2] row_mask:0xf bank_mask:0xf
	v_mov_b32_dpp v215, v211 quad_perm:[1,0,3,2] row_mask:0xf bank_mask:0xf
	v_perm_b32 v216, v212, v208, v221
	v_perm_b32 v217, v213, v209, v221
	v_perm_b32 v218, v214, v210, v221
	v_perm_b32 v219, v215, v211, v221
	global_store_dword v220, v216, s[4:5]
	global_store_dword v220, v217, s[4:5] offset:64
	global_store_dword v223, v218, s[4:5]
	global_store_dword v223, v219, s[4:5] offset:64
	s_mul_i32 s0, s1, 56
	v_add_u32_e32 v220, s0, v222
	s_mul_i32 s0, s1, 58
	v_add_u32_e32 v223, s0, v222
	v_cvt_pk_bf16_f32 v208, v94, v95
	v_cvt_pk_bf16_f32 v209, v78, v79
	v_cvt_pk_bf16_f32 v210, v96, v97
	v_cvt_pk_bf16_f32 v211, v80, v81
	v_mov_b32_dpp v212, v208 quad_perm:[1,0,3,2] row_mask:0xf bank_mask:0xf
	v_mov_b32_dpp v213, v209 quad_perm:[1,0,3,2] row_mask:0xf bank_mask:0xf
	v_mov_b32_dpp v214, v210 quad_perm:[1,0,3,2] row_mask:0xf bank_mask:0xf
	v_mov_b32_dpp v215, v211 quad_perm:[1,0,3,2] row_mask:0xf bank_mask:0xf
	v_perm_b32 v216, v212, v208, v221
	v_perm_b32 v217, v213, v209, v221
	v_perm_b32 v218, v214, v210, v221
	v_perm_b32 v219, v215, v211, v221
	global_store_dword v220, v216, s[4:5]
	global_store_dword v220, v217, s[4:5] offset:64
	global_store_dword v223, v218, s[4:5]
	global_store_dword v223, v219, s[4:5] offset:64
	s_mul_i32 s0, s1, 64
	v_add_u32_e32 v220, s0, v222
	s_mul_i32 s0, s1, 66
	v_add_u32_e32 v223, s0, v222
	v_cvt_pk_bf16_f32 v208, v50, v51
	v_cvt_pk_bf16_f32 v209, v34, v35
	v_cvt_pk_bf16_f32 v210, v52, v53
	v_cvt_pk_bf16_f32 v211, v36, v37
	v_mov_b32_dpp v212, v208 quad_perm:[1,0,3,2] row_mask:0xf bank_mask:0xf
	v_mov_b32_dpp v213, v209 quad_perm:[1,0,3,2] row_mask:0xf bank_mask:0xf
	v_mov_b32_dpp v214, v210 quad_perm:[1,0,3,2] row_mask:0xf bank_mask:0xf
	v_mov_b32_dpp v215, v211 quad_perm:[1,0,3,2] row_mask:0xf bank_mask:0xf
	v_perm_b32 v216, v212, v208, v221
	v_perm_b32 v217, v213, v209, v221
	v_perm_b32 v218, v214, v210, v221
	v_perm_b32 v219, v215, v211, v221
	global_store_dword v220, v216, s[4:5]
	global_store_dword v220, v217, s[4:5] offset:64
	global_store_dword v223, v218, s[4:5]
	global_store_dword v223, v219, s[4:5] offset:64
	s_mul_i32 s0, s1, 72
	v_add_u32_e32 v220, s0, v222
	s_mul_i32 s0, s1, 74
	v_add_u32_e32 v223, s0, v222
	v_cvt_pk_bf16_f32 v208, v54, v55
	v_cvt_pk_bf16_f32 v209, v38, v39
	v_cvt_pk_bf16_f32 v210, v56, v57
	v_cvt_pk_bf16_f32 v211, v40, v41
	v_mov_b32_dpp v212, v208 quad_perm:[1,0,3,2] row_mask:0xf bank_mask:0xf
	v_mov_b32_dpp v213, v209 quad_perm:[1,0,3,2] row_mask:0xf bank_mask:0xf
	v_mov_b32_dpp v214, v210 quad_perm:[1,0,3,2] row_mask:0xf bank_mask:0xf
	v_mov_b32_dpp v215, v211 quad_perm:[1,0,3,2] row_mask:0xf bank_mask:0xf
	v_perm_b32 v216, v212, v208, v221
	v_perm_b32 v217, v213, v209, v221
	v_perm_b32 v218, v214, v210, v221
	v_perm_b32 v219, v215, v211, v221
	global_store_dword v220, v216, s[4:5]
	global_store_dword v220, v217, s[4:5] offset:64
	global_store_dword v223, v218, s[4:5]
	global_store_dword v223, v219, s[4:5] offset:64
	s_mul_i32 s0, s1, 80
	v_add_u32_e32 v220, s0, v222
	s_mul_i32 s0, s1, 82
	v_add_u32_e32 v223, s0, v222
	v_cvt_pk_bf16_f32 v208, v58, v59
	v_cvt_pk_bf16_f32 v209, v42, v43
	v_cvt_pk_bf16_f32 v210, v60, v61
	v_cvt_pk_bf16_f32 v211, v44, v45
	v_mov_b32_dpp v212, v208 quad_perm:[1,0,3,2] row_mask:0xf bank_mask:0xf
	v_mov_b32_dpp v213, v209 quad_perm:[1,0,3,2] row_mask:0xf bank_mask:0xf
	v_mov_b32_dpp v214, v210 quad_perm:[1,0,3,2] row_mask:0xf bank_mask:0xf
	v_mov_b32_dpp v215, v211 quad_perm:[1,0,3,2] row_mask:0xf bank_mask:0xf
	v_perm_b32 v216, v212, v208, v221
; DI int crow(int reg, int h5) { return (reg & 3) + 8 * (reg >> 2) + 4 * h5; }
; template <int MTW> DI void gemm_in_phase(const Params& p, int l, int bid, int nb, char* smem) {
;     ...
; #pragma unroll
;       for (int mt = 0; mt < MTW; ++mt)
; #pragma unroll
;         for (int nt = 0; nt < 2; ++nt)
; #pragma unroll
;           for (int i = 0; i < 16; ++i) {
;             const int row = row0 + wr * (32 * MTW) + mt * 32 + crow(i, h5);
;             dstb[(size_t)row * ld + cb + nt * 32 + c] = f2bf(acc[mt][nt][i]);
;           }
	v_perm_b32 v217, v213, v209, v221
	v_perm_b32 v218, v214, v210, v221
	v_perm_b32 v219, v215, v211, v221
	global_store_dword v220, v216, s[4:5]
	global_store_dword v220, v217, s[4:5] offset:64
	global_store_dword v223, v218, s[4:5]
	global_store_dword v223, v219, s[4:5] offset:64
	s_mul_i32 s0, s1, 88
	v_add_u32_e32 v220, s0, v222
	s_mul_i32 s0, s1, 90
	v_add_u32_e32 v223, s0, v222
	v_cvt_pk_bf16_f32 v208, v62, v63
	v_cvt_pk_bf16_f32 v209, v46, v47
	v_cvt_pk_bf16_f32 v210, v64, v65
	v_cvt_pk_bf16_f32 v211, v48, v49
	v_mov_b32_dpp v212, v208 quad_perm:[1,0,3,2] row_mask:0xf bank_mask:0xf
	v_mov_b32_dpp v213, v209 quad_perm:[1,0,3,2] row_mask:0xf bank_mask:0xf
	v_mov_b32_dpp v214, v210 quad_perm:[1,0,3,2] row_mask:0xf bank_mask:0xf
	v_mov_b32_dpp v215, v211 quad_perm:[1,0,3,2] row_mask:0xf bank_mask:0xf
	v_perm_b32 v216, v212, v208, v221
	v_perm_b32 v217, v213, v209, v221
	v_perm_b32 v218, v214, v210, v221
	v_perm_b32 v219, v215, v211, v221
	global_store_dword v220, v216, s[4:5]
	global_store_dword v220, v217, s[4:5] offset:64
	global_store_dword v223, v218, s[4:5]
	global_store_dword v223, v219, s[4:5] offset:64
	s_mul_i32 s0, s1, 96
	v_add_u32_e32 v220, s0, v222
	s_mul_i32 s0, s1, 98
	v_add_u32_e32 v223, s0, v222
	v_cvt_pk_bf16_f32 v208, v18, v19
	v_cvt_pk_bf16_f32 v209, v2, v3
	v_cvt_pk_bf16_f32 v210, v20, v21
	v_cvt_pk_bf16_f32 v211, v4, v5
	v_mov_b32_dpp v212, v208 quad_perm:[1,0,3,2] row_mask:0xf bank_mask:0xf
	v_mov_b32_dpp v213, v209 quad_perm:[1,0,3,2] row_mask:0xf bank_mask:0xf
	v_mov_b32_dpp v214, v210 quad_perm:[1,0,3,2] row_mask:0xf bank_mask:0xf
	v_mov_b32_dpp v215, v211 quad_perm:[1,0,3,2] row_mask:0xf bank_mask:0xf
	v_perm_b32 v216, v212, v208, v221
	v_perm_b32 v217, v213, v209, v221
	v_perm_b32 v218, v214, v210, v221
	v_perm_b32 v219, v215, v211, v221
	global_store_dword v220, v216, s[4:5]
	global_store_dword v220, v217, s[4:5] offset:64
	global_store_dword v223, v218, s[4:5]
	global_store_dword v223, v219, s[4:5] offset:64
	s_mul_i32 s0, s1, 104
	v_add_u32_e32 v220, s0, v222
	s_mul_i32 s0, s1, 106
	v_add_u32_e32 v223, s0, v222
	v_cvt_pk_bf16_f32 v208, v22, v23
	v_cvt_pk_bf16_f32 v209, v6, v7
	v_cvt_pk_bf16_f32 v210, v24, v25
	v_cvt_pk_bf16_f32 v211, v8, v9
	v_mov_b32_dpp v212, v208 quad_perm:[1,0,3,2] row_mask:0xf bank_mask:0xf
	v_mov_b32_dpp v213, v209 quad_perm:[1,0,3,2] row_mask:0xf bank_mask:0xf
	v_mov_b32_dpp v214, v210 quad_perm:[1,0,3,2] row_mask:0xf bank_mask:0xf
	v_mov_b32_dpp v215, v211 quad_perm:[1,0,3,2] row_mask:0xf bank_mask:0xf
	v_perm_b32 v216, v212, v208, v221
	v_perm_b32 v217, v213, v209, v221
	v_perm_b32 v218, v214, v210, v221
	v_perm_b32 v219, v215, v211, v221
	global_store_dword v220, v216, s[4:5]
	global_store_dword v220, v217, s[4:5] offset:64
	global_store_dword v223, v218, s[4:5]
	global_store_dword v223, v219, s[4:5] offset:64
	s_mul_i32 s0, s1, 112
	v_add_u32_e32 v220, s0, v222
	s_mul_i32 s0, s1, 114
	v_add_u32_e32 v223, s0, v222
	v_cvt_pk_bf16_f32 v208, v26, v27
	v_cvt_pk_bf16_f32 v209, v10, v11
	v_cvt_pk_bf16_f32 v210, v28, v29
	v_cvt_pk_bf16_f32 v211, v12, v13
	v_mov_b32_dpp v212, v208 quad_perm:[1,0,3,2] row_mask:0xf bank_mask:0xf
	v_mov_b32_dpp v213, v209 quad_perm:[1,0,3,2] row_mask:0xf bank_mask:0xf
	v_mov_b32_dpp v214, v210 quad_perm:[1,0,3,2] row_mask:0xf bank_mask:0xf
	v_mov_b32_dpp v215, v211 quad_perm:[1,0,3,2] row_mask:0xf bank_mask:0xf
	v_perm_b32 v216, v212, v208, v221
	v_perm_b32 v217, v213, v209, v221
	v_perm_b32 v218, v214, v210, v221
	v_perm_b32 v219, v215, v211, v221
	global_store_dword v220, v216, s[4:5]
	global_store_dword v220, v217, s[4:5] offset:64
	global_store_dword v223, v218, s[4:5]
	global_store_dword v223, v219, s[4:5] offset:64
	s_mul_i32 s0, s1, 120
	v_add_u32_e32 v220, s0, v222
	s_mul_i32 s0, s1, 122
	v_add_u32_e32 v223, s0, v222
	v_cvt_pk_bf16_f32 v208, v30, v31
	v_cvt_pk_bf16_f32 v209, v14, v15
	v_cvt_pk_bf16_f32 v210, v32, v33
	v_cvt_pk_bf16_f32 v211, v16, v17
	v_mov_b32_dpp v212, v208 quad_perm:[1,0,3,2] row_mask:0xf bank_mask:0xf
	v_mov_b32_dpp v213, v209 quad_perm:[1,0,3,2] row_mask:0xf bank_mask:0xf
	v_mov_b32_dpp v214, v210 quad_perm:[1,0,3,2] row_mask:0xf bank_mask:0xf
	v_mov_b32_dpp v215, v211 quad_perm:[1,0,3,2] row_mask:0xf bank_mask:0xf
	v_perm_b32 v216, v212, v208, v221
	v_perm_b32 v217, v213, v209, v221
	v_perm_b32 v218, v214, v210, v221
	v_perm_b32 v219, v215, v211, v221
	global_store_dword v220, v216, s[4:5]
	global_store_dword v220, v217, s[4:5] offset:64
	global_store_dword v223, v218, s[4:5]
	global_store_dword v223, v219, s[4:5] offset:64
	s_mov_b64 s[4:5], 0
